# compress_item finalize: the eight k_gain loads fetched once as two dwordx4 instead of eight load+wait blocks
# speedup vs baseline: 1.0041x; 1.0041x over previous
; DI u32x4 pack8(const float* f) { u32x4 w; w.x = pk2(f[0], f[1]); w.y = pk2(f[2], f[3]); w.z = pk2(f[4], f[5]); w.w = pk2(f[6], f[7]); return w; }
; DI float red8(float x) { x = red4(x); x = dpp_add<0x141>(x); return x; }
; DI void compress_item(const Args& a, int l, int item, LAS unsigned char* lds) {
;     ...
;         if (kv == 0) {
;             float ss = 0.f;
; #pragma unroll
;             for (int i = 0; i < 8; ++i) ss += v[i] * v[i];
;             ss = red8(ss);
;             const float rstd = rsqrtf(ss * (1.f / 64.f) + 1e-6f);
;             const float* gn = a.in[I_KGAIN] + (l * 3 + 0) * 64 + d0;
; #pragma unroll
;             for (int i = 0; i < 8; ++i) v[i] = (n == 255) ? 0.f : v[i] * rstd * gn[i];
;             *(u32x4*)((bf16_t*)(a.ws + WS_KCN) + ((size_t)bg * 256 + n) * 64 + d0) = pack8(v);
.LBB0_608:
	s_andn2_b64 vcc, exec, s[6:7]
	s_cbranch_vccnz .LBB0_598
	s_waitcnt lgkmcnt(1)
	v_pk_mul_f32 v[10:11], v[4:5], v[4:5]
	v_pk_mul_f32 v[14:15], v[6:7], v[6:7]
	v_add_f32_e32 v9, v10, v11
	v_add_f32_e32 v9, v9, v14
	s_waitcnt lgkmcnt(0)
	v_pk_mul_f32 v[16:17], v[0:1], v[0:1]
	v_add_f32_e32 v9, v9, v15
	v_add_f32_e32 v9, v9, v16
	v_pk_mul_f32 v[18:19], v[2:3], v[2:3]
	v_add_f32_e32 v9, v9, v17
	v_add_f32_e32 v9, v9, v18
	v_add_f32_e32 v9, v9, v19
	s_mov_b32 s2, 0x800000
	v_mov_b32_e32 v13, 0
	v_add_f32_dpp v9, v9, v9 quad_perm:[1,0,3,2] row_mask:0xf bank_mask:0xf bound_ctrl:1
	v_mov_b32_e32 v14, 0
	s_nop 0
	v_add_f32_dpp v9, v9, v9 quad_perm:[2,3,0,1] row_mask:0xf bank_mask:0xf bound_ctrl:1
	s_nop 1
	v_add_f32_dpp v9, v9, v9 row_half_mirror row_mask:0xf bank_mask:0xf bound_ctrl:1
	v_fmamk_f32 v9, v9, 0x3c800000, v154
	v_mul_f32_e32 v10, 0x4b800000, v9
	v_cmp_gt_f32_e32 vcc, s2, v9
	s_movk_i32 s2, 0xff
	s_nop 0
	v_cndmask_b32_e32 v9, v9, v10, vcc
	v_rsq_f32_e32 v9, v9
	s_nop 0
	v_mul_f32_e32 v10, 0x45800000, v9
	v_cndmask_b32_e32 v9, v9, v10, vcc
	v_lshl_add_u64 v[10:11], s[0:1], 0, v[128:129]
	v_cmp_ne_u32_e32 vcc, s2, v8
	global_load_dwordx4 v[24:27], v[10:11], off
	global_load_dwordx4 v[28:31], v[10:11], off offset:16
	s_waitcnt vmcnt(0)
	s_and_saveexec_b64 s[2:3], vcc
	s_cbranch_execz .LBB0_611
	v_mul_f32_e32 v4, v4, v9
	v_mul_f32_e32 v14, v4, v24
.LBB0_611:
	s_or_b64 exec, exec, s[2:3]
	s_and_saveexec_b64 s[2:3], vcc
	s_cbranch_execz .LBB0_613
	v_mul_f32_e32 v5, v5, v9
	v_mul_f32_e32 v13, v5, v25
.LBB0_613:
	s_or_b64 exec, exec, s[2:3]
	v_mov_b32_e32 v4, 0
	v_mov_b32_e32 v5, 0
	s_and_saveexec_b64 s[2:3], vcc
	s_cbranch_execz .LBB0_615
	v_mul_f32_e32 v6, v6, v9
	v_mul_f32_e32 v5, v6, v26
.LBB0_615:
	s_or_b64 exec, exec, s[2:3]
	s_and_saveexec_b64 s[2:3], vcc
	s_cbranch_execz .LBB0_617
	v_mul_f32_e32 v6, v7, v9
	v_mul_f32_e32 v4, v6, v27
.LBB0_617:
	s_or_b64 exec, exec, s[2:3]
	v_mov_b32_e32 v6, 0
	v_mov_b32_e32 v7, 0
	s_and_saveexec_b64 s[2:3], vcc
	s_cbranch_execz .LBB0_619
	v_mul_f32_e32 v0, v0, v9
	v_mul_f32_e32 v7, v0, v28
.LBB0_619:
	s_or_b64 exec, exec, s[2:3]
	s_and_saveexec_b64 s[2:3], vcc
	s_cbranch_execz .LBB0_621
	v_mul_f32_e32 v1, v1, v9
	v_mul_f32_e32 v6, v1, v29
.LBB0_621:
	s_or_b64 exec, exec, s[2:3]
	v_mov_b32_e32 v0, 0
	v_mov_b32_e32 v1, 0
	s_and_saveexec_b64 s[2:3], vcc
	s_cbranch_execz .LBB0_623
	v_mul_f32_e32 v2, v2, v9
	v_mul_f32_e32 v1, v2, v30
.LBB0_623:
	s_or_b64 exec, exec, s[2:3]
	s_and_saveexec_b64 s[2:3], vcc
	s_cbranch_execz .LBB0_597
	v_mul_f32_e32 v2, v3, v9
	v_mul_f32_e32 v0, v2, v31
	s_branch .LBB0_597
